# PC1/PC2 K-loops: mid-burst s_setprio 0/1 pair removed (burst edge flips kept), on top of v92
# baseline (speedup 1.0000x reference)
; #define PG8_STAGE(bufoff, gbase, voff) do { _Pragma("unroll") for (int _i = 0; _i < 2; ++_i) \
;         __builtin_amdgcn_global_load_lds((const unsigned*)((const char*)(gbase) + (voff)[_i]), (LAS unsigned*)(lds + (bufoff) + ldsw + _i * 8192), 16, 0, 0); } while (0)
; #define PG8_LDA(dst, b, h) do { _Pragma("unroll") for (int m = 0; m < 4; ++m) _Pragma("unroll") for (int k = 0; k < 2; ++k) dst[m][k] = *(const LAS bf16x8*)(lds + PG8_SA(b, h) + aoff + m * 2048 + k * 1024); } while (0)
; #define PG8_LDB(dst, b, h) do { _Pragma("unroll") for (int n = 0; n < 2; ++n) _Pragma("unroll") for (int k = 0; k < 2; ++k) dst[n][k] = *(const LAS bf16x8*)(lds + PG8_SB(b, h) + boff + n * 2048 + k * 1024); } while (0)
; #define PG8_MMA(ai, bj, At, Bt) do { __builtin_amdgcn_s_setprio(1); _Pragma("unroll") for (int m = 0; m < 4; ++m) _Pragma("unroll") for (int n = 0; n < 2; ++n) _Pragma("unroll") for (int k = 0; k < 2; ++k) \
;         acc[ai][bj][m][n] = __builtin_amdgcn_mfma_f32_16x16x32_bf16(Bt[n][k], At[m][k], acc[ai][bj][m][n], 0, 0, 0); __builtin_amdgcn_s_setprio(0); } while (0)
; #define PG8_WAIT_V(n) asm volatile("s_waitcnt vmcnt(" #n ")" ::: "memory")
; #define PG8_WAIT_L(n) asm volatile("s_waitcnt lgkmcnt(" #n ")" ::: "memory")
; #define PG8_BAR __builtin_amdgcn_s_barrier()
; #define PG8_SCHED __builtin_amdgcn_sched_barrier(0)
; template <class Epi, class Sched>
; __device__ __forceinline__ void gemm_phase(LAS unsigned char* lds, const Sched& S, const Epi& E, bool natural = false) {
;     ...
;             const bool last = (t == nt - 2);
;             const char* a1 = cA + (size_t)(t + 1) * kstep;
;             const char* a2 = last ? nA : cA + (size_t)(t + 2) * kstep; const char* b2 = last ? nB : cB + (size_t)(t + 2) * kstep;
;             const char* a3 = a2 + kstep; const char* b3 = b2 + kstep;
;             if constexpr (Epi::MIDHOOK) { if (t == nt / 2) E.mid(acc, cur, wr, wc, fr, fq); }
;             PG8_LDB(B0, 0, 0); PG8_LDB(B1, 0, 1); PG8_SCHED; PG8_LDA(At, 0, 0); PG8_STAGE(PG8_SA(1, 1), a1 + hstep, voffA);
;             PG8_WAIT_V(8); PG8_WAIT_L(0); PG8_BAR; PG8_MMA(0, 0, At, B0); PG8_MMA(0, 1, At, B1); PG8_BAR; PG8_SCHED;
;             PG8_LDA(At, 0, 1); PG8_STAGE(PG8_SB(0, 0), b2, voffB0); PG8_STAGE(PG8_SB(0, 1), b2, voffB1); PG8_STAGE(PG8_SA(0, 0), a2, voffA);
.LBB0_491:
	s_add_u32 s28, s24, s26
	s_addc_u32 s29, s25, s27
	s_add_u32 s28, s28, 0x100
	s_addc_u32 s29, s29, 0
	s_add_u32 s60, s57, s26
	s_addc_u32 s61, s58, s27
	s_cmpk_eq_i32 s26, 0x700
	s_cselect_b32 s60, s56, s60
	s_cselect_b32 s31, s17, s29
	s_cselect_b32 s30, s19, s28
	s_cselect_b32 s61, s55, s61
	s_add_u32 s28, s60, 0x80
	s_addc_u32 s29, s61, 0
	s_add_i32 s68, 0, 0x10000
	v_add_u32_e32 v140, s68, v186
	v_add_u32_e32 v156, s54, v186
	ds_read_b128 v[128:131], v140
	ds_read_b128 v[132:135], v140 offset:1024
	ds_read_b128 v[136:139], v140 offset:2048
	ds_read_b128 v[140:143], v140 offset:3072
	ds_read_b128 v[144:147], v156
	ds_read_b128 v[148:151], v156 offset:1024
	ds_read_b128 v[152:155], v156 offset:2048
	ds_read_b128 v[156:159], v156 offset:3072
	v_lshl_add_u64 v[224:225], v[160:161], 0, s[26:27]
	s_add_i32 m0, s39, 0xc000
	ds_read_b128 v[192:195], v188
	ds_read_b128 v[196:199], v188 offset:1024
	ds_read_b128 v[200:203], v188 offset:2048
	ds_read_b128 v[204:207], v188 offset:3072
	ds_read_b128 v[208:211], v188 offset:4096
	ds_read_b128 v[212:215], v188 offset:5120
	ds_read_b128 v[216:219], v188 offset:6144
	ds_read_b128 v[220:223], v188 offset:7168
	global_load_lds_dwordx4 v[224:225], off
	v_lshl_add_u64 v[224:225], v[162:163], 0, s[26:27]
	s_add_i32 m0, s39, 0xe000
	s_nop 0
	global_load_lds_dwordx4 v[224:225], off
	s_waitcnt vmcnt(8)
	s_waitcnt lgkmcnt(0)
	s_barrier
	s_setprio 1
	s_waitcnt lgkmcnt(0)
	v_mfma_f32_16x16x32_bf16 v[124:127], v[128:131], v[192:195], v[124:127]
	v_mfma_f32_16x16x32_bf16 v[120:123], v[136:139], v[192:195], v[120:123]
	v_mfma_f32_16x16x32_bf16 v[108:111], v[128:131], v[200:203], v[108:111]
	v_mfma_f32_16x16x32_bf16 v[104:107], v[136:139], v[200:203], v[104:107]
	v_mfma_f32_16x16x32_bf16 v[92:95], v[128:131], v[208:211], v[92:95]
	v_mfma_f32_16x16x32_bf16 v[88:91], v[136:139], v[208:211], v[88:91]
	v_mfma_f32_16x16x32_bf16 v[76:79], v[128:131], v[216:219], v[76:79]
	v_mfma_f32_16x16x32_bf16 v[72:75], v[136:139], v[216:219], v[72:75]
	v_mfma_f32_16x16x32_bf16 v[124:127], v[132:135], v[196:199], v[124:127]
	v_mfma_f32_16x16x32_bf16 v[120:123], v[140:143], v[196:199], v[120:123]
	v_mfma_f32_16x16x32_bf16 v[108:111], v[132:135], v[204:207], v[108:111]
	v_mfma_f32_16x16x32_bf16 v[104:107], v[140:143], v[204:207], v[104:107]
	v_mfma_f32_16x16x32_bf16 v[92:95], v[132:135], v[212:215], v[92:95]
	v_mfma_f32_16x16x32_bf16 v[88:91], v[140:143], v[212:215], v[88:91]
	v_mfma_f32_16x16x32_bf16 v[76:79], v[132:135], v[220:223], v[76:79]
	v_mfma_f32_16x16x32_bf16 v[72:75], v[140:143], v[220:223], v[72:75]
	v_mfma_f32_16x16x32_bf16 v[116:119], v[144:147], v[192:195], v[116:119]
	v_mfma_f32_16x16x32_bf16 v[112:115], v[152:155], v[192:195], v[112:115]
	v_mfma_f32_16x16x32_bf16 v[100:103], v[144:147], v[200:203], v[100:103]
	v_mfma_f32_16x16x32_bf16 v[96:99], v[152:155], v[200:203], v[96:99]
	v_mfma_f32_16x16x32_bf16 v[84:87], v[144:147], v[208:211], v[84:87]
	v_mfma_f32_16x16x32_bf16 v[80:83], v[152:155], v[208:211], v[80:83]
	v_mfma_f32_16x16x32_bf16 v[68:71], v[144:147], v[216:219], v[68:71]
	v_mfma_f32_16x16x32_bf16 v[64:67], v[152:155], v[216:219], v[64:67]
	v_mfma_f32_16x16x32_bf16 v[116:119], v[148:151], v[196:199], v[116:119]
	v_mfma_f32_16x16x32_bf16 v[112:115], v[156:159], v[196:199], v[112:115]
	v_mfma_f32_16x16x32_bf16 v[100:103], v[148:151], v[204:207], v[100:103]
	v_mfma_f32_16x16x32_bf16 v[96:99], v[156:159], v[204:207], v[96:99]
	v_mfma_f32_16x16x32_bf16 v[84:87], v[148:151], v[212:215], v[84:87]
	v_mfma_f32_16x16x32_bf16 v[80:83], v[156:159], v[212:215], v[80:83]
	v_mfma_f32_16x16x32_bf16 v[68:71], v[148:151], v[220:223], v[68:71]
	v_mfma_f32_16x16x32_bf16 v[64:67], v[156:159], v[220:223], v[64:67]
	s_setprio 0
	s_barrier
	s_add_i32 s68, s68, s36
	v_lshl_add_u64 v[224:225], s[60:61], 0, v[172:173]
	s_mov_b32 m0, s68
	ds_read_b128 v[192:195], v188 offset:16384
	ds_read_b128 v[196:199], v188 offset:17408
	ds_read_b128 v[200:203], v188 offset:18432
	ds_read_b128 v[204:207], v188 offset:19456
	ds_read_b128 v[208:211], v188 offset:20480
	ds_read_b128 v[212:215], v188 offset:21504
	ds_read_b128 v[216:219], v188 offset:22528
	ds_read_b128 v[220:223], v188 offset:23552
	global_load_lds_dwordx4 v[224:225], off
	v_lshl_add_u64 v[226:227], s[60:61], 0, v[166:167]
	s_add_i32 m0, s68, 0x2000
	s_add_i32 s68, s54, s36
	global_load_lds_dwordx4 v[226:227], off
	v_lshl_add_u64 v[228:229], s[60:61], 0, v[170:171]
	s_mov_b32 m0, s68
	v_lshl_add_u64 v[230:231], s[30:31], 0, v[168:169]
	global_load_lds_dwordx4 v[228:229], off
	v_lshl_add_u64 v[228:229], s[60:61], 0, v[164:165]
	s_add_i32 m0, s68, 0x2000
	s_nop 0
	global_load_lds_dwordx4 v[228:229], off
	v_lshl_add_u64 v[228:229], s[30:31], 0, v[174:175]
	s_mov_b32 m0, s39
	s_nop 0
	global_load_lds_dwordx4 v[228:229], off
	s_mov_b32 m0, s40
	s_nop 0
	global_load_lds_dwordx4 v[230:231], off
	s_waitcnt vmcnt(8)
	s_waitcnt lgkmcnt(0)
	s_barrier
; #define PG8_STAGE(bufoff, gbase, voff) do { _Pragma("unroll") for (int _i = 0; _i < 2; ++_i) \
;         __builtin_amdgcn_global_load_lds((const unsigned*)((const char*)(gbase) + (voff)[_i]), (LAS unsigned*)(lds + (bufoff) + ldsw + _i * 8192), 16, 0, 0); } while (0)
; #define PG8_LDA(dst, b, h) do { _Pragma("unroll") for (int m = 0; m < 4; ++m) _Pragma("unroll") for (int k = 0; k < 2; ++k) dst[m][k] = *(const LAS bf16x8*)(lds + PG8_SA(b, h) + aoff + m * 2048 + k * 1024); } while (0)
; #define PG8_LDB(dst, b, h) do { _Pragma("unroll") for (int n = 0; n < 2; ++n) _Pragma("unroll") for (int k = 0; k < 2; ++k) dst[n][k] = *(const LAS bf16x8*)(lds + PG8_SB(b, h) + boff + n * 2048 + k * 1024); } while (0)
; #define PG8_MMA(ai, bj, At, Bt) do { __builtin_amdgcn_s_setprio(1); _Pragma("unroll") for (int m = 0; m < 4; ++m) _Pragma("unroll") for (int n = 0; n < 2; ++n) _Pragma("unroll") for (int k = 0; k < 2; ++k) \
;         acc[ai][bj][m][n] = __builtin_amdgcn_mfma_f32_16x16x32_bf16(Bt[n][k], At[m][k], acc[ai][bj][m][n], 0, 0, 0); __builtin_amdgcn_s_setprio(0); } while (0)
; #define PG8_WAIT_V(n) asm volatile("s_waitcnt vmcnt(" #n ")" ::: "memory")
; #define PG8_WAIT_L(n) asm volatile("s_waitcnt lgkmcnt(" #n ")" ::: "memory")
; #define PG8_BAR __builtin_amdgcn_s_barrier()
; #define PG8_SCHED __builtin_amdgcn_sched_barrier(0)
; template <class Epi, class Sched>
; __device__ __forceinline__ void gemm_phase(LAS unsigned char* lds, const Sched& S, const Epi& E, bool natural = false) {
;     ...
;             PG8_WAIT_V(8); PG8_WAIT_L(0); PG8_BAR; PG8_MMA(1, 0, At, B0); PG8_MMA(1, 1, At, B1); PG8_BAR; PG8_SCHED;
;             PG8_LDB(B0, 1, 0); PG8_LDB(B1, 1, 1); PG8_SCHED; PG8_LDA(At, 1, 0); PG8_STAGE(PG8_SA(0, 1), a2 + hstep, voffA);
;             PG8_WAIT_V(8); PG8_WAIT_L(0); PG8_BAR; PG8_MMA(0, 0, At, B0); PG8_MMA(0, 1, At, B1); PG8_BAR; PG8_SCHED;
	s_setprio 1
	s_waitcnt lgkmcnt(0)
	v_mfma_f32_16x16x32_bf16 v[60:63], v[128:131], v[192:195], v[60:63]
	v_mfma_f32_16x16x32_bf16 v[56:59], v[136:139], v[192:195], v[56:59]
	v_mfma_f32_16x16x32_bf16 v[44:47], v[128:131], v[200:203], v[44:47]
	v_mfma_f32_16x16x32_bf16 v[40:43], v[136:139], v[200:203], v[40:43]
	v_mfma_f32_16x16x32_bf16 v[28:31], v[128:131], v[208:211], v[28:31]
	v_mfma_f32_16x16x32_bf16 v[24:27], v[136:139], v[208:211], v[24:27]
	v_mfma_f32_16x16x32_bf16 v[12:15], v[128:131], v[216:219], v[12:15]
	v_mfma_f32_16x16x32_bf16 v[8:11], v[136:139], v[216:219], v[8:11]
	v_mfma_f32_16x16x32_bf16 v[60:63], v[132:135], v[196:199], v[60:63]
	v_mfma_f32_16x16x32_bf16 v[56:59], v[140:143], v[196:199], v[56:59]
	v_mfma_f32_16x16x32_bf16 v[44:47], v[132:135], v[204:207], v[44:47]
	v_mfma_f32_16x16x32_bf16 v[40:43], v[140:143], v[204:207], v[40:43]
	v_mfma_f32_16x16x32_bf16 v[28:31], v[132:135], v[212:215], v[28:31]
	v_mfma_f32_16x16x32_bf16 v[24:27], v[140:143], v[212:215], v[24:27]
	v_mfma_f32_16x16x32_bf16 v[12:15], v[132:135], v[220:223], v[12:15]
	v_mfma_f32_16x16x32_bf16 v[8:11], v[140:143], v[220:223], v[8:11]
	v_mfma_f32_16x16x32_bf16 v[52:55], v[144:147], v[192:195], v[52:55]
	v_mfma_f32_16x16x32_bf16 v[48:51], v[152:155], v[192:195], v[48:51]
	v_mfma_f32_16x16x32_bf16 v[36:39], v[144:147], v[200:203], v[36:39]
	v_mfma_f32_16x16x32_bf16 v[32:35], v[152:155], v[200:203], v[32:35]
	v_mfma_f32_16x16x32_bf16 v[20:23], v[144:147], v[208:211], v[20:23]
	v_mfma_f32_16x16x32_bf16 v[16:19], v[152:155], v[208:211], v[16:19]
	v_mfma_f32_16x16x32_bf16 v[4:7], v[144:147], v[216:219], v[4:7]
	v_mfma_f32_16x16x32_bf16 v[0:3], v[152:155], v[216:219], v[0:3]
	v_mfma_f32_16x16x32_bf16 v[52:55], v[148:151], v[196:199], v[52:55]
	v_mfma_f32_16x16x32_bf16 v[48:51], v[156:159], v[196:199], v[48:51]
	v_mfma_f32_16x16x32_bf16 v[36:39], v[148:151], v[204:207], v[36:39]
	v_mfma_f32_16x16x32_bf16 v[32:35], v[156:159], v[204:207], v[32:35]
	v_mfma_f32_16x16x32_bf16 v[20:23], v[148:151], v[212:215], v[20:23]
	v_mfma_f32_16x16x32_bf16 v[16:19], v[156:159], v[212:215], v[16:19]
	v_mfma_f32_16x16x32_bf16 v[4:7], v[148:151], v[220:223], v[4:7]
	v_mfma_f32_16x16x32_bf16 v[0:3], v[156:159], v[220:223], v[0:3]
	s_setprio 0
	s_barrier
	s_add_i32 s60, 0, 0x18000
	s_add_i32 s61, 0, 0x1c000
	v_add_u32_e32 v140, s60, v186
	v_add_u32_e32 v156, s61, v186
	ds_read_b128 v[128:131], v140
	ds_read_b128 v[132:135], v140 offset:1024
	ds_read_b128 v[136:139], v140 offset:2048
	ds_read_b128 v[140:143], v140 offset:3072
	ds_read_b128 v[144:147], v156
	ds_read_b128 v[148:151], v156 offset:1024
	ds_read_b128 v[152:155], v156 offset:2048
	ds_read_b128 v[156:159], v156 offset:3072
	s_add_u32 s30, s30, 0x40000
	s_addc_u32 s31, s31, 0
	s_mov_b32 m0, s41
	v_lshl_add_u64 v[232:233], s[30:31], 0, v[174:175]
	ds_read_b128 v[192:195], v188 offset:32768
	ds_read_b128 v[196:199], v188 offset:33792
	ds_read_b128 v[200:203], v188 offset:34816
	ds_read_b128 v[204:207], v188 offset:35840
	ds_read_b128 v[208:211], v188 offset:36864
	ds_read_b128 v[212:215], v188 offset:37888
	ds_read_b128 v[216:219], v188 offset:38912
	ds_read_b128 v[220:223], v188 offset:39936
	global_load_lds_dwordx4 v[232:233], off
	v_lshl_add_u64 v[232:233], s[30:31], 0, v[168:169]
	s_mov_b32 m0, s42
	s_nop 0
	global_load_lds_dwordx4 v[232:233], off
	s_waitcnt vmcnt(8)
	s_waitcnt lgkmcnt(0)
	s_barrier
	s_setprio 1
	s_waitcnt lgkmcnt(0)
	v_mfma_f32_16x16x32_bf16 v[124:127], v[128:131], v[192:195], v[124:127]
	v_mfma_f32_16x16x32_bf16 v[120:123], v[136:139], v[192:195], v[120:123]
	v_mfma_f32_16x16x32_bf16 v[108:111], v[128:131], v[200:203], v[108:111]
	v_mfma_f32_16x16x32_bf16 v[104:107], v[136:139], v[200:203], v[104:107]
	v_mfma_f32_16x16x32_bf16 v[92:95], v[128:131], v[208:211], v[92:95]
	v_mfma_f32_16x16x32_bf16 v[88:91], v[136:139], v[208:211], v[88:91]
	v_mfma_f32_16x16x32_bf16 v[76:79], v[128:131], v[216:219], v[76:79]
	v_mfma_f32_16x16x32_bf16 v[72:75], v[136:139], v[216:219], v[72:75]
	v_mfma_f32_16x16x32_bf16 v[124:127], v[132:135], v[196:199], v[124:127]
	v_mfma_f32_16x16x32_bf16 v[120:123], v[140:143], v[196:199], v[120:123]
	v_mfma_f32_16x16x32_bf16 v[108:111], v[132:135], v[204:207], v[108:111]
	v_mfma_f32_16x16x32_bf16 v[104:107], v[140:143], v[204:207], v[104:107]
	v_mfma_f32_16x16x32_bf16 v[92:95], v[132:135], v[212:215], v[92:95]
	v_mfma_f32_16x16x32_bf16 v[88:91], v[140:143], v[212:215], v[88:91]
	v_mfma_f32_16x16x32_bf16 v[76:79], v[132:135], v[220:223], v[76:79]
	v_mfma_f32_16x16x32_bf16 v[72:75], v[140:143], v[220:223], v[72:75]
	v_mfma_f32_16x16x32_bf16 v[116:119], v[144:147], v[192:195], v[116:119]
	v_mfma_f32_16x16x32_bf16 v[112:115], v[152:155], v[192:195], v[112:115]
	v_mfma_f32_16x16x32_bf16 v[100:103], v[144:147], v[200:203], v[100:103]
	v_mfma_f32_16x16x32_bf16 v[96:99], v[152:155], v[200:203], v[96:99]
	v_mfma_f32_16x16x32_bf16 v[84:87], v[144:147], v[208:211], v[84:87]
	v_mfma_f32_16x16x32_bf16 v[80:83], v[152:155], v[208:211], v[80:83]
	v_mfma_f32_16x16x32_bf16 v[68:71], v[144:147], v[216:219], v[68:71]
	v_mfma_f32_16x16x32_bf16 v[64:67], v[152:155], v[216:219], v[64:67]
	v_mfma_f32_16x16x32_bf16 v[116:119], v[148:151], v[196:199], v[116:119]
	v_mfma_f32_16x16x32_bf16 v[112:115], v[156:159], v[196:199], v[112:115]
	v_mfma_f32_16x16x32_bf16 v[100:103], v[148:151], v[204:207], v[100:103]
	v_mfma_f32_16x16x32_bf16 v[96:99], v[156:159], v[204:207], v[96:99]
	v_mfma_f32_16x16x32_bf16 v[84:87], v[148:151], v[212:215], v[84:87]
	v_mfma_f32_16x16x32_bf16 v[80:83], v[156:159], v[212:215], v[80:83]
	v_mfma_f32_16x16x32_bf16 v[68:71], v[148:151], v[220:223], v[68:71]
	v_mfma_f32_16x16x32_bf16 v[64:67], v[156:159], v[220:223], v[64:67]
	s_setprio 0
	s_barrier
; #define PG8_STAGE(bufoff, gbase, voff) do { _Pragma("unroll") for (int _i = 0; _i < 2; ++_i) \
;         __builtin_amdgcn_global_load_lds((const unsigned*)((const char*)(gbase) + (voff)[_i]), (LAS unsigned*)(lds + (bufoff) + ldsw + _i * 8192), 16, 0, 0); } while (0)
; #define PG8_LDA(dst, b, h) do { _Pragma("unroll") for (int m = 0; m < 4; ++m) _Pragma("unroll") for (int k = 0; k < 2; ++k) dst[m][k] = *(const LAS bf16x8*)(lds + PG8_SA(b, h) + aoff + m * 2048 + k * 1024); } while (0)
; #define PG8_MMA(ai, bj, At, Bt) do { __builtin_amdgcn_s_setprio(1); _Pragma("unroll") for (int m = 0; m < 4; ++m) _Pragma("unroll") for (int n = 0; n < 2; ++n) _Pragma("unroll") for (int k = 0; k < 2; ++k) \
;         acc[ai][bj][m][n] = __builtin_amdgcn_mfma_f32_16x16x32_bf16(Bt[n][k], At[m][k], acc[ai][bj][m][n], 0, 0, 0); __builtin_amdgcn_s_setprio(0); } while (0)
; #define PG8_WAIT_V(n) asm volatile("s_waitcnt vmcnt(" #n ")" ::: "memory")
; #define PG8_WAIT_L(n) asm volatile("s_waitcnt lgkmcnt(" #n ")" ::: "memory")
; #define PG8_BAR __builtin_amdgcn_s_barrier()
; #define PG8_SCHED __builtin_amdgcn_sched_barrier(0)
; template <class Epi, class Sched>
; __device__ __forceinline__ void gemm_phase(LAS unsigned char* lds, const Sched& S, const Epi& E, bool natural = false) {
;     ...
;             PG8_LDA(At, 1, 1); PG8_STAGE(PG8_SB(1, 0), b3, voffB0); PG8_STAGE(PG8_SB(1, 1), b3, voffB1); PG8_STAGE(PG8_SA(1, 0), a3, voffA);
;             PG8_WAIT_V(8); PG8_WAIT_L(0); PG8_BAR; PG8_MMA(1, 0, At, B0); PG8_MMA(1, 1, At, B1); PG8_BAR; PG8_SCHED;
	s_add_i32 s30, s60, s36
	v_lshl_add_u64 v[224:225], v[224:225], 0, s[12:13]
	s_mov_b32 m0, s30
	ds_read_b128 v[192:195], v188 offset:49152
	ds_read_b128 v[196:199], v188 offset:50176
	ds_read_b128 v[200:203], v188 offset:51200
	ds_read_b128 v[204:207], v188 offset:52224
	ds_read_b128 v[208:211], v188 offset:53248
	ds_read_b128 v[212:215], v188 offset:54272
	ds_read_b128 v[216:219], v188 offset:55296
	ds_read_b128 v[220:223], v188 offset:56320
	global_load_lds_dwordx4 v[224:225], off
	v_lshl_add_u64 v[224:225], v[226:227], 0, s[12:13]
	s_add_i32 m0, s30, 0x2000
	s_add_i32 s30, s61, s36
	global_load_lds_dwordx4 v[224:225], off
	v_lshl_add_u64 v[224:225], s[28:29], 0, v[170:171]
	s_mov_b32 m0, s30
	s_nop 0
	global_load_lds_dwordx4 v[224:225], off
	v_lshl_add_u64 v[224:225], s[28:29], 0, v[164:165]
	s_add_i32 m0, s30, 0x2000
	s_nop 0
	global_load_lds_dwordx4 v[224:225], off
	v_lshl_add_u64 v[224:225], v[228:229], 0, s[12:13]
	s_mov_b32 m0, s46
	s_nop 0
	global_load_lds_dwordx4 v[224:225], off
	v_lshl_add_u64 v[224:225], v[230:231], 0, s[12:13]
	s_mov_b32 m0, s47
	s_nop 0
	global_load_lds_dwordx4 v[224:225], off
	s_waitcnt vmcnt(8)
	s_waitcnt lgkmcnt(0)
	s_barrier
	s_setprio 1
	s_waitcnt lgkmcnt(0)
	v_mfma_f32_16x16x32_bf16 v[60:63], v[128:131], v[192:195], v[60:63]
	v_mfma_f32_16x16x32_bf16 v[56:59], v[136:139], v[192:195], v[56:59]
	v_mfma_f32_16x16x32_bf16 v[44:47], v[128:131], v[200:203], v[44:47]
	v_mfma_f32_16x16x32_bf16 v[40:43], v[136:139], v[200:203], v[40:43]
	v_mfma_f32_16x16x32_bf16 v[28:31], v[128:131], v[208:211], v[28:31]
	v_mfma_f32_16x16x32_bf16 v[24:27], v[136:139], v[208:211], v[24:27]
	v_mfma_f32_16x16x32_bf16 v[12:15], v[128:131], v[216:219], v[12:15]
	v_mfma_f32_16x16x32_bf16 v[8:11], v[136:139], v[216:219], v[8:11]
	v_mfma_f32_16x16x32_bf16 v[60:63], v[132:135], v[196:199], v[60:63]
	v_mfma_f32_16x16x32_bf16 v[56:59], v[140:143], v[196:199], v[56:59]
	v_mfma_f32_16x16x32_bf16 v[44:47], v[132:135], v[204:207], v[44:47]
	v_mfma_f32_16x16x32_bf16 v[40:43], v[140:143], v[204:207], v[40:43]
	v_mfma_f32_16x16x32_bf16 v[28:31], v[132:135], v[212:215], v[28:31]
	v_mfma_f32_16x16x32_bf16 v[24:27], v[140:143], v[212:215], v[24:27]
	v_mfma_f32_16x16x32_bf16 v[12:15], v[132:135], v[220:223], v[12:15]
	v_mfma_f32_16x16x32_bf16 v[8:11], v[140:143], v[220:223], v[8:11]
	v_mfma_f32_16x16x32_bf16 v[52:55], v[144:147], v[192:195], v[52:55]
	v_mfma_f32_16x16x32_bf16 v[48:51], v[152:155], v[192:195], v[48:51]
	v_mfma_f32_16x16x32_bf16 v[36:39], v[144:147], v[200:203], v[36:39]
	v_mfma_f32_16x16x32_bf16 v[32:35], v[152:155], v[200:203], v[32:35]
	v_mfma_f32_16x16x32_bf16 v[20:23], v[144:147], v[208:211], v[20:23]
	v_mfma_f32_16x16x32_bf16 v[16:19], v[152:155], v[208:211], v[16:19]
	v_mfma_f32_16x16x32_bf16 v[4:7], v[144:147], v[216:219], v[4:7]
	v_mfma_f32_16x16x32_bf16 v[0:3], v[152:155], v[216:219], v[0:3]
	v_mfma_f32_16x16x32_bf16 v[52:55], v[148:151], v[196:199], v[52:55]
	v_mfma_f32_16x16x32_bf16 v[48:51], v[156:159], v[196:199], v[48:51]
	v_mfma_f32_16x16x32_bf16 v[36:39], v[148:151], v[204:207], v[36:39]
	v_mfma_f32_16x16x32_bf16 v[32:35], v[156:159], v[204:207], v[32:35]
	v_mfma_f32_16x16x32_bf16 v[20:23], v[148:151], v[212:215], v[20:23]
	v_mfma_f32_16x16x32_bf16 v[16:19], v[156:159], v[212:215], v[16:19]
	v_mfma_f32_16x16x32_bf16 v[4:7], v[148:151], v[220:223], v[4:7]
	v_mfma_f32_16x16x32_bf16 v[0:3], v[156:159], v[220:223], v[0:3]
	s_setprio 0
	s_barrier
	s_add_i32 s59, s59, 2
	s_add_u32 s26, s26, 0x100
	s_addc_u32 s27, s27, 0
	s_cmp_gt_u32 s59, 13
	s_cbranch_scc1 .LBB0_494

; #define PG8_STAGE(bufoff, gbase, voff) do { _Pragma("unroll") for (int _i = 0; _i < 2; ++_i) \
;         __builtin_amdgcn_global_load_lds((const unsigned*)((const char*)(gbase) + (voff)[_i]), (LAS unsigned*)(lds + (bufoff) + ldsw + _i * 8192), 16, 0, 0); } while (0)
; #define PG8_LDA(dst, b, h) do { _Pragma("unroll") for (int m = 0; m < 4; ++m) _Pragma("unroll") for (int k = 0; k < 2; ++k) dst[m][k] = *(const LAS bf16x8*)(lds + PG8_SA(b, h) + aoff + m * 2048 + k * 1024); } while (0)
; #define PG8_LDB(dst, b, h) do { _Pragma("unroll") for (int n = 0; n < 2; ++n) _Pragma("unroll") for (int k = 0; k < 2; ++k) dst[n][k] = *(const LAS bf16x8*)(lds + PG8_SB(b, h) + boff + n * 2048 + k * 1024); } while (0)
; #define PG8_MMA(ai, bj, At, Bt) do { __builtin_amdgcn_s_setprio(1); _Pragma("unroll") for (int m = 0; m < 4; ++m) _Pragma("unroll") for (int n = 0; n < 2; ++n) _Pragma("unroll") for (int k = 0; k < 2; ++k) \
;         acc[ai][bj][m][n] = __builtin_amdgcn_mfma_f32_16x16x32_bf16(Bt[n][k], At[m][k], acc[ai][bj][m][n], 0, 0, 0); __builtin_amdgcn_s_setprio(0); } while (0)
; #define PG8_WAIT_V(n) asm volatile("s_waitcnt vmcnt(" #n ")" ::: "memory")
; #define PG8_WAIT_L(n) asm volatile("s_waitcnt lgkmcnt(" #n ")" ::: "memory")
; template <class Epi, class Sched>
; __device__ __forceinline__ void gemm_phase(LAS unsigned char* lds, const Sched& S, const Epi& E, bool natural = false) {
;     ...
;         const bool has_next = S.next(ui + 1, nxt);
;         const char* nA = cA; const char* nB = cB; if (has_next) S.ptrs(nxt, nA, nB);
;         for (int t = 0; t < nt; t += 2) {
;             const bool last = (t == nt - 2);
;             const char* a1 = cA + (size_t)(t + 1) * kstep;
;             const char* a2 = last ? nA : cA + (size_t)(t + 2) * kstep; const char* b2 = last ? nB : cB + (size_t)(t + 2) * kstep;
;             const char* a3 = a2 + kstep; const char* b3 = b2 + kstep;
;             if constexpr (Epi::MIDHOOK) { if (t == nt / 2) E.mid(acc, cur, wr, wc, fr, fq); }
;             PG8_LDB(B0, 0, 0); PG8_LDB(B1, 0, 1); PG8_SCHED; PG8_LDA(At, 0, 0); PG8_STAGE(PG8_SA(1, 1), a1 + hstep, voffA);
;             PG8_WAIT_V(8); PG8_WAIT_L(0); PG8_BAR; PG8_MMA(0, 0, At, B0); PG8_MMA(0, 1, At, B1); PG8_BAR; PG8_SCHED;
;             PG8_LDA(At, 0, 1); PG8_STAGE(PG8_SB(0, 0), b2, voffB0); PG8_STAGE(PG8_SB(0, 1), b2, voffB1); PG8_STAGE(PG8_SA(0, 0), a2, voffA);
.LBB0_563:
	s_ashr_i32 s15, s14, 31
	s_ashr_i32 s13, s12, 31
	s_lshl_b64 s[16:17], s[14:15], 19
	s_lshl_b64 s[18:19], s[12:13], 19
	s_add_u32 s16, s3, s16
	s_addc_u32 s17, s28, s17
	s_add_u32 s18, s29, s18
	s_addc_u32 s19, s30, s19
	s_and_b64 s[24:25], s[0:1], exec
	s_cselect_b32 s13, s17, s21
	s_cselect_b32 s15, s16, s20
	s_cselect_b32 s26, s19, s23
	s_cselect_b32 s27, s18, s22
	s_add_u32 s20, s20, 0x40080
	s_addc_u32 s21, s21, 0
	s_add_u32 s54, s22, 0x100
	s_addc_u32 s55, s23, 0
	s_mov_b32 s56, -2
	ds_read_b128 v[150:153], v156
	ds_read_b128 v[160:163], v156 offset:1024
	ds_read_b128 v[164:167], v156 offset:2048
	ds_read_b128 v[168:171], v156 offset:3072
	ds_read_b128 v[172:175], v157
	ds_read_b128 v[176:179], v157 offset:1024
	ds_read_b128 v[180:183], v157 offset:2048
	ds_read_b128 v[184:187], v157 offset:3072
	s_add_u32 s22, s20, 0xfffc0080
	s_addc_u32 s23, s21, -1
	s_cmp_eq_u32 s56, 12
	s_cselect_b32 s25, s13, s23
	s_cselect_b32 s24, s15, s22
	s_cselect_b32 s23, s26, s55
	s_cselect_b32 s22, s27, s54
	v_lshl_add_u64 v[220:221], s[20:21], 0, v[142:143]
	s_add_i32 m0, s35, 0xc000
	ds_read_b128 v[188:191], v158
	ds_read_b128 v[192:195], v158 offset:1024
	ds_read_b128 v[196:199], v158 offset:2048
	ds_read_b128 v[200:203], v158 offset:3072
	ds_read_b128 v[204:207], v158 offset:4096
	ds_read_b128 v[208:211], v158 offset:5120
	ds_read_b128 v[212:215], v158 offset:6144
	ds_read_b128 v[216:219], v158 offset:7168
	global_load_lds_dwordx4 v[220:221], off
	v_lshl_add_u64 v[220:221], s[20:21], 0, v[144:145]
	s_add_i32 m0, s35, 0xe000
	s_nop 0
	global_load_lds_dwordx4 v[220:221], off
	s_waitcnt vmcnt(8)
	s_waitcnt lgkmcnt(0)
	s_barrier
	s_setprio 1
	s_waitcnt lgkmcnt(0)
	v_mfma_f32_16x16x32_bf16 v[124:127], v[150:153], v[188:191], 0
	v_mfma_f32_16x16x32_bf16 v[120:123], v[164:167], v[188:191], 0
	v_mfma_f32_16x16x32_bf16 v[116:119], v[150:153], v[196:199], 0
	v_mfma_f32_16x16x32_bf16 v[112:115], v[164:167], v[196:199], 0
	v_mfma_f32_16x16x32_bf16 v[104:107], v[150:153], v[204:207], 0
	v_mfma_f32_16x16x32_bf16 v[96:99], v[164:167], v[204:207], 0
	v_mfma_f32_16x16x32_bf16 v[88:91], v[150:153], v[212:215], 0
	v_mfma_f32_16x16x32_bf16 v[80:83], v[164:167], v[212:215], 0
	v_mfma_f32_16x16x32_bf16 v[124:127], v[160:163], v[192:195], v[124:127]
	v_mfma_f32_16x16x32_bf16 v[120:123], v[168:171], v[192:195], v[120:123]
	v_mfma_f32_16x16x32_bf16 v[116:119], v[160:163], v[200:203], v[116:119]
	v_mfma_f32_16x16x32_bf16 v[112:115], v[168:171], v[200:203], v[112:115]
	v_mfma_f32_16x16x32_bf16 v[104:107], v[160:163], v[208:211], v[104:107]
	v_mfma_f32_16x16x32_bf16 v[96:99], v[168:171], v[208:211], v[96:99]
	v_mfma_f32_16x16x32_bf16 v[88:91], v[160:163], v[216:219], v[88:91]
	v_mfma_f32_16x16x32_bf16 v[80:83], v[168:171], v[216:219], v[80:83]
	v_mfma_f32_16x16x32_bf16 v[108:111], v[172:175], v[188:191], 0
	v_mfma_f32_16x16x32_bf16 v[100:103], v[180:183], v[188:191], 0
	v_mfma_f32_16x16x32_bf16 v[92:95], v[172:175], v[196:199], 0
	v_mfma_f32_16x16x32_bf16 v[84:87], v[180:183], v[196:199], 0
	v_mfma_f32_16x16x32_bf16 v[76:79], v[172:175], v[204:207], 0
	v_mfma_f32_16x16x32_bf16 v[72:75], v[180:183], v[204:207], 0
	v_mfma_f32_16x16x32_bf16 v[68:71], v[172:175], v[212:215], 0
	v_mfma_f32_16x16x32_bf16 v[64:67], v[180:183], v[212:215], 0
	v_mfma_f32_16x16x32_bf16 v[108:111], v[176:179], v[192:195], v[108:111]
	v_mfma_f32_16x16x32_bf16 v[100:103], v[184:187], v[192:195], v[100:103]
	v_mfma_f32_16x16x32_bf16 v[92:95], v[176:179], v[200:203], v[92:95]
	v_mfma_f32_16x16x32_bf16 v[84:87], v[184:187], v[200:203], v[84:87]
	v_mfma_f32_16x16x32_bf16 v[76:79], v[176:179], v[208:211], v[76:79]
	v_mfma_f32_16x16x32_bf16 v[72:75], v[184:187], v[208:211], v[72:75]
	v_mfma_f32_16x16x32_bf16 v[68:71], v[176:179], v[216:219], v[68:71]
	v_mfma_f32_16x16x32_bf16 v[64:67], v[184:187], v[216:219], v[64:67]
	s_setprio 0
	s_barrier
	s_add_i32 s57, s44, s31
	v_lshl_add_u64 v[220:221], s[22:23], 0, v[136:137]
	s_mov_b32 m0, s57
	ds_read_b128 v[188:191], v158 offset:16384
	ds_read_b128 v[192:195], v158 offset:17408
	ds_read_b128 v[196:199], v158 offset:18432
	ds_read_b128 v[200:203], v158 offset:19456
	ds_read_b128 v[204:207], v158 offset:20480
	ds_read_b128 v[208:211], v158 offset:21504
	ds_read_b128 v[212:215], v158 offset:22528
	ds_read_b128 v[216:219], v158 offset:23552
	global_load_lds_dwordx4 v[220:221], off
	v_lshl_add_u64 v[222:223], s[22:23], 0, v[130:131]
	s_add_i32 m0, s57, 0x2000
	s_add_i32 s57, s45, s31
	global_load_lds_dwordx4 v[222:223], off
	v_lshl_add_u64 v[224:225], s[22:23], 0, v[134:135]
	s_mov_b32 m0, s57
	v_lshl_add_u64 v[226:227], s[24:25], 0, v[132:133]
	global_load_lds_dwordx4 v[224:225], off
	v_lshl_add_u64 v[224:225], s[22:23], 0, v[128:129]
	s_add_i32 m0, s57, 0x2000
	s_nop 0
	global_load_lds_dwordx4 v[224:225], off
	v_lshl_add_u64 v[224:225], s[24:25], 0, v[138:139]
	s_mov_b32 m0, s35
	s_nop 0
	global_load_lds_dwordx4 v[224:225], off
	s_mov_b32 m0, s36
	s_nop 0
	global_load_lds_dwordx4 v[226:227], off
	s_waitcnt vmcnt(8)
	s_waitcnt lgkmcnt(0)
	s_barrier
; #define PG8_STAGE(bufoff, gbase, voff) do { _Pragma("unroll") for (int _i = 0; _i < 2; ++_i) \
;         __builtin_amdgcn_global_load_lds((const unsigned*)((const char*)(gbase) + (voff)[_i]), (LAS unsigned*)(lds + (bufoff) + ldsw + _i * 8192), 16, 0, 0); } while (0)
; #define PG8_LDA(dst, b, h) do { _Pragma("unroll") for (int m = 0; m < 4; ++m) _Pragma("unroll") for (int k = 0; k < 2; ++k) dst[m][k] = *(const LAS bf16x8*)(lds + PG8_SA(b, h) + aoff + m * 2048 + k * 1024); } while (0)
; #define PG8_LDB(dst, b, h) do { _Pragma("unroll") for (int n = 0; n < 2; ++n) _Pragma("unroll") for (int k = 0; k < 2; ++k) dst[n][k] = *(const LAS bf16x8*)(lds + PG8_SB(b, h) + boff + n * 2048 + k * 1024); } while (0)
; #define PG8_MMA(ai, bj, At, Bt) do { __builtin_amdgcn_s_setprio(1); _Pragma("unroll") for (int m = 0; m < 4; ++m) _Pragma("unroll") for (int n = 0; n < 2; ++n) _Pragma("unroll") for (int k = 0; k < 2; ++k) \
;         acc[ai][bj][m][n] = __builtin_amdgcn_mfma_f32_16x16x32_bf16(Bt[n][k], At[m][k], acc[ai][bj][m][n], 0, 0, 0); __builtin_amdgcn_s_setprio(0); } while (0)
; #define PG8_WAIT_V(n) asm volatile("s_waitcnt vmcnt(" #n ")" ::: "memory")
; #define PG8_WAIT_L(n) asm volatile("s_waitcnt lgkmcnt(" #n ")" ::: "memory")
; #define PG8_BAR __builtin_amdgcn_s_barrier()
; #define PG8_SCHED __builtin_amdgcn_sched_barrier(0)
; template <class Epi, class Sched>
; __device__ __forceinline__ void gemm_phase(LAS unsigned char* lds, const Sched& S, const Epi& E, bool natural = false) {
;     ...
;             PG8_WAIT_V(8); PG8_WAIT_L(0); PG8_BAR; PG8_MMA(1, 0, At, B0); PG8_MMA(1, 1, At, B1); PG8_BAR; PG8_SCHED;
;             PG8_LDB(B0, 1, 0); PG8_LDB(B1, 1, 1); PG8_SCHED; PG8_LDA(At, 1, 0); PG8_STAGE(PG8_SA(0, 1), a2 + hstep, voffA);
;             PG8_WAIT_V(8); PG8_WAIT_L(0); PG8_BAR; PG8_MMA(0, 0, At, B0); PG8_MMA(0, 1, At, B1); PG8_BAR; PG8_SCHED;
	s_setprio 1
	s_waitcnt lgkmcnt(0)
	v_mfma_f32_16x16x32_bf16 v[60:63], v[150:153], v[188:191], 0
	v_mfma_f32_16x16x32_bf16 v[56:59], v[164:167], v[188:191], 0
	v_mfma_f32_16x16x32_bf16 v[52:55], v[150:153], v[196:199], 0
	v_mfma_f32_16x16x32_bf16 v[48:51], v[164:167], v[196:199], 0
	v_mfma_f32_16x16x32_bf16 v[44:47], v[150:153], v[204:207], 0
	v_mfma_f32_16x16x32_bf16 v[32:35], v[164:167], v[204:207], 0
	v_mfma_f32_16x16x32_bf16 v[20:23], v[150:153], v[212:215], 0
	v_mfma_f32_16x16x32_bf16 v[8:11], v[164:167], v[212:215], 0
	v_mfma_f32_16x16x32_bf16 v[60:63], v[160:163], v[192:195], v[60:63]
	v_mfma_f32_16x16x32_bf16 v[56:59], v[168:171], v[192:195], v[56:59]
	v_mfma_f32_16x16x32_bf16 v[52:55], v[160:163], v[200:203], v[52:55]
	v_mfma_f32_16x16x32_bf16 v[48:51], v[168:171], v[200:203], v[48:51]
	v_mfma_f32_16x16x32_bf16 v[44:47], v[160:163], v[208:211], v[44:47]
	v_mfma_f32_16x16x32_bf16 v[32:35], v[168:171], v[208:211], v[32:35]
	v_mfma_f32_16x16x32_bf16 v[20:23], v[160:163], v[216:219], v[20:23]
	v_mfma_f32_16x16x32_bf16 v[8:11], v[168:171], v[216:219], v[8:11]
	v_mfma_f32_16x16x32_bf16 v[40:43], v[172:175], v[188:191], 0
	v_mfma_f32_16x16x32_bf16 v[36:39], v[180:183], v[188:191], 0
	v_mfma_f32_16x16x32_bf16 v[28:31], v[172:175], v[196:199], 0
	v_mfma_f32_16x16x32_bf16 v[24:27], v[180:183], v[196:199], 0
	v_mfma_f32_16x16x32_bf16 v[16:19], v[172:175], v[204:207], 0
	v_mfma_f32_16x16x32_bf16 v[12:15], v[180:183], v[204:207], 0
	v_mfma_f32_16x16x32_bf16 v[4:7], v[172:175], v[212:215], 0
	v_mfma_f32_16x16x32_bf16 v[0:3], v[180:183], v[212:215], 0
	v_mfma_f32_16x16x32_bf16 v[40:43], v[176:179], v[192:195], v[40:43]
	v_mfma_f32_16x16x32_bf16 v[36:39], v[184:187], v[192:195], v[36:39]
	v_mfma_f32_16x16x32_bf16 v[28:31], v[176:179], v[200:203], v[28:31]
	v_mfma_f32_16x16x32_bf16 v[24:27], v[184:187], v[200:203], v[24:27]
	v_mfma_f32_16x16x32_bf16 v[16:19], v[176:179], v[208:211], v[16:19]
	v_mfma_f32_16x16x32_bf16 v[12:15], v[184:187], v[208:211], v[12:15]
	v_mfma_f32_16x16x32_bf16 v[4:7], v[176:179], v[216:219], v[4:7]
	v_mfma_f32_16x16x32_bf16 v[0:3], v[184:187], v[216:219], v[0:3]
	s_setprio 0
	s_barrier
	s_add_i32 s57, 0, 0x18000
	v_add_u32_e32 v140, s57, v154
	s_add_i32 s58, 0, 0x1c000
	ds_read_b128 v[150:153], v140
	ds_read_b128 v[160:163], v140 offset:1024
	ds_read_b128 v[164:167], v140 offset:2048
	ds_read_b128 v[168:171], v140 offset:3072
	v_add_u32_e32 v140, s58, v154
	ds_read_b128 v[172:175], v140
	ds_read_b128 v[176:179], v140 offset:1024
	ds_read_b128 v[180:183], v140 offset:2048
	ds_read_b128 v[184:187], v140 offset:3072
	s_add_u32 s24, s24, 0x40000
	s_addc_u32 s25, s25, 0
	s_mov_b32 m0, s37
	v_lshl_add_u64 v[228:229], s[24:25], 0, v[138:139]
	ds_read_b128 v[188:191], v158 offset:32768
	ds_read_b128 v[192:195], v158 offset:33792
	ds_read_b128 v[196:199], v158 offset:34816
	ds_read_b128 v[200:203], v158 offset:35840
	ds_read_b128 v[204:207], v158 offset:36864
	ds_read_b128 v[208:211], v158 offset:37888
	ds_read_b128 v[212:215], v158 offset:38912
	ds_read_b128 v[216:219], v158 offset:39936
	global_load_lds_dwordx4 v[228:229], off
	v_lshl_add_u64 v[228:229], s[24:25], 0, v[132:133]
	s_mov_b32 m0, s38
	s_nop 0
	global_load_lds_dwordx4 v[228:229], off
	s_waitcnt vmcnt(8)
	s_waitcnt lgkmcnt(0)
	s_barrier
	s_setprio 1
	s_waitcnt lgkmcnt(0)
	v_mfma_f32_16x16x32_bf16 v[124:127], v[150:153], v[188:191], v[124:127]
	v_mfma_f32_16x16x32_bf16 v[120:123], v[164:167], v[188:191], v[120:123]
	v_mfma_f32_16x16x32_bf16 v[116:119], v[150:153], v[196:199], v[116:119]
	v_mfma_f32_16x16x32_bf16 v[112:115], v[164:167], v[196:199], v[112:115]
	v_mfma_f32_16x16x32_bf16 v[104:107], v[150:153], v[204:207], v[104:107]
	v_mfma_f32_16x16x32_bf16 v[96:99], v[164:167], v[204:207], v[96:99]
	v_mfma_f32_16x16x32_bf16 v[88:91], v[150:153], v[212:215], v[88:91]
	v_mfma_f32_16x16x32_bf16 v[80:83], v[164:167], v[212:215], v[80:83]
	v_mfma_f32_16x16x32_bf16 v[124:127], v[160:163], v[192:195], v[124:127]
	v_mfma_f32_16x16x32_bf16 v[120:123], v[168:171], v[192:195], v[120:123]
	v_mfma_f32_16x16x32_bf16 v[116:119], v[160:163], v[200:203], v[116:119]
	v_mfma_f32_16x16x32_bf16 v[112:115], v[168:171], v[200:203], v[112:115]
	v_mfma_f32_16x16x32_bf16 v[104:107], v[160:163], v[208:211], v[104:107]
	v_mfma_f32_16x16x32_bf16 v[96:99], v[168:171], v[208:211], v[96:99]
	v_mfma_f32_16x16x32_bf16 v[88:91], v[160:163], v[216:219], v[88:91]
	v_mfma_f32_16x16x32_bf16 v[80:83], v[168:171], v[216:219], v[80:83]
	v_mfma_f32_16x16x32_bf16 v[108:111], v[172:175], v[188:191], v[108:111]
	v_mfma_f32_16x16x32_bf16 v[100:103], v[180:183], v[188:191], v[100:103]
	v_mfma_f32_16x16x32_bf16 v[92:95], v[172:175], v[196:199], v[92:95]
	v_mfma_f32_16x16x32_bf16 v[84:87], v[180:183], v[196:199], v[84:87]
	v_mfma_f32_16x16x32_bf16 v[76:79], v[172:175], v[204:207], v[76:79]
	v_mfma_f32_16x16x32_bf16 v[72:75], v[180:183], v[204:207], v[72:75]
	v_mfma_f32_16x16x32_bf16 v[68:71], v[172:175], v[212:215], v[68:71]
	v_mfma_f32_16x16x32_bf16 v[64:67], v[180:183], v[212:215], v[64:67]
	v_mfma_f32_16x16x32_bf16 v[108:111], v[176:179], v[192:195], v[108:111]
	v_mfma_f32_16x16x32_bf16 v[100:103], v[184:187], v[192:195], v[100:103]
	v_mfma_f32_16x16x32_bf16 v[92:95], v[176:179], v[200:203], v[92:95]
	v_mfma_f32_16x16x32_bf16 v[84:87], v[184:187], v[200:203], v[84:87]
	v_mfma_f32_16x16x32_bf16 v[76:79], v[176:179], v[208:211], v[76:79]
	v_mfma_f32_16x16x32_bf16 v[72:75], v[184:187], v[208:211], v[72:75]
	v_mfma_f32_16x16x32_bf16 v[68:71], v[176:179], v[216:219], v[68:71]
	v_mfma_f32_16x16x32_bf16 v[64:67], v[184:187], v[216:219], v[64:67]
	s_setprio 0
	s_barrier
; #define PG8_STAGE(bufoff, gbase, voff) do { _Pragma("unroll") for (int _i = 0; _i < 2; ++_i) \
;         __builtin_amdgcn_global_load_lds((const unsigned*)((const char*)(gbase) + (voff)[_i]), (LAS unsigned*)(lds + (bufoff) + ldsw + _i * 8192), 16, 0, 0); } while (0)
; #define PG8_LDA(dst, b, h) do { _Pragma("unroll") for (int m = 0; m < 4; ++m) _Pragma("unroll") for (int k = 0; k < 2; ++k) dst[m][k] = *(const LAS bf16x8*)(lds + PG8_SA(b, h) + aoff + m * 2048 + k * 1024); } while (0)
; #define PG8_LDB(dst, b, h) do { _Pragma("unroll") for (int n = 0; n < 2; ++n) _Pragma("unroll") for (int k = 0; k < 2; ++k) dst[n][k] = *(const LAS bf16x8*)(lds + PG8_SB(b, h) + boff + n * 2048 + k * 1024); } while (0)
; #define PG8_MMA(ai, bj, At, Bt) do { __builtin_amdgcn_s_setprio(1); _Pragma("unroll") for (int m = 0; m < 4; ++m) _Pragma("unroll") for (int n = 0; n < 2; ++n) _Pragma("unroll") for (int k = 0; k < 2; ++k) \
;         acc[ai][bj][m][n] = __builtin_amdgcn_mfma_f32_16x16x32_bf16(Bt[n][k], At[m][k], acc[ai][bj][m][n], 0, 0, 0); __builtin_amdgcn_s_setprio(0); } while (0)
; #define PG8_WAIT_V(n) asm volatile("s_waitcnt vmcnt(" #n ")" ::: "memory")
; #define PG8_WAIT_L(n) asm volatile("s_waitcnt lgkmcnt(" #n ")" ::: "memory")
; #define PG8_BAR __builtin_amdgcn_s_barrier()
; #define PG8_SCHED __builtin_amdgcn_sched_barrier(0)
; template <class Epi, class Sched>
; __device__ __forceinline__ void gemm_phase(LAS unsigned char* lds, const Sched& S, const Epi& E, bool natural = false) {
;     ...
;             PG8_LDB(B0, 0, 0); PG8_LDB(B1, 0, 1); PG8_SCHED; PG8_LDA(At, 0, 0); PG8_STAGE(PG8_SA(1, 1), a1 + hstep, voffA);
;             PG8_WAIT_V(8); PG8_WAIT_L(0); PG8_BAR; PG8_MMA(0, 0, At, B0); PG8_MMA(0, 1, At, B1); PG8_BAR; PG8_SCHED;
;     ...
;             PG8_LDA(At, 1, 1); PG8_STAGE(PG8_SB(1, 0), b3, voffB0); PG8_STAGE(PG8_SB(1, 1), b3, voffB1); PG8_STAGE(PG8_SA(1, 0), a3, voffA);
;             PG8_WAIT_V(8); PG8_WAIT_L(0); PG8_BAR; PG8_MMA(1, 0, At, B0); PG8_MMA(1, 1, At, B1); PG8_BAR; PG8_SCHED;
	s_add_u32 s22, s22, 0x80
	s_addc_u32 s23, s23, 0
	s_add_i32 s24, s57, s31
	v_lshl_add_u64 v[220:221], v[220:221], 0, s[8:9]
	s_mov_b32 m0, s24
	ds_read_b128 v[188:191], v158 offset:49152
	ds_read_b128 v[192:195], v158 offset:50176
	ds_read_b128 v[196:199], v158 offset:51200
	ds_read_b128 v[200:203], v158 offset:52224
	ds_read_b128 v[204:207], v158 offset:53248
	ds_read_b128 v[208:211], v158 offset:54272
	ds_read_b128 v[212:215], v158 offset:55296
	ds_read_b128 v[216:219], v158 offset:56320
	global_load_lds_dwordx4 v[220:221], off
	v_lshl_add_u64 v[220:221], v[222:223], 0, s[8:9]
	s_add_i32 m0, s24, 0x2000
	s_add_i32 s24, s58, s31
	global_load_lds_dwordx4 v[220:221], off
	v_lshl_add_u64 v[220:221], s[22:23], 0, v[134:135]
	s_mov_b32 m0, s24
	s_nop 0
	global_load_lds_dwordx4 v[220:221], off
	v_lshl_add_u64 v[220:221], s[22:23], 0, v[128:129]
	s_add_i32 m0, s24, 0x2000
	s_nop 0
	global_load_lds_dwordx4 v[220:221], off
	v_lshl_add_u64 v[220:221], v[224:225], 0, s[8:9]
	s_mov_b32 m0, s41
	s_nop 0
	global_load_lds_dwordx4 v[220:221], off
	v_lshl_add_u64 v[220:221], v[226:227], 0, s[8:9]
	s_mov_b32 m0, s42
	s_nop 0
	global_load_lds_dwordx4 v[220:221], off
	s_waitcnt vmcnt(8)
	s_waitcnt lgkmcnt(0)
	s_barrier
	s_setprio 1
	s_waitcnt lgkmcnt(0)
	v_mfma_f32_16x16x32_bf16 v[60:63], v[150:153], v[188:191], v[60:63]
	v_mfma_f32_16x16x32_bf16 v[56:59], v[164:167], v[188:191], v[56:59]
	v_mfma_f32_16x16x32_bf16 v[52:55], v[150:153], v[196:199], v[52:55]
	v_mfma_f32_16x16x32_bf16 v[48:51], v[164:167], v[196:199], v[48:51]
	v_mfma_f32_16x16x32_bf16 v[44:47], v[150:153], v[204:207], v[44:47]
	v_mfma_f32_16x16x32_bf16 v[32:35], v[164:167], v[204:207], v[32:35]
	v_mfma_f32_16x16x32_bf16 v[20:23], v[150:153], v[212:215], v[20:23]
	v_mfma_f32_16x16x32_bf16 v[8:11], v[164:167], v[212:215], v[8:11]
	v_mfma_f32_16x16x32_bf16 v[60:63], v[160:163], v[192:195], v[60:63]
	v_mfma_f32_16x16x32_bf16 v[56:59], v[168:171], v[192:195], v[56:59]
	v_mfma_f32_16x16x32_bf16 v[52:55], v[160:163], v[200:203], v[52:55]
	v_mfma_f32_16x16x32_bf16 v[48:51], v[168:171], v[200:203], v[48:51]
	v_mfma_f32_16x16x32_bf16 v[44:47], v[160:163], v[208:211], v[44:47]
	v_mfma_f32_16x16x32_bf16 v[32:35], v[168:171], v[208:211], v[32:35]
	v_mfma_f32_16x16x32_bf16 v[20:23], v[160:163], v[216:219], v[20:23]
	v_mfma_f32_16x16x32_bf16 v[8:11], v[168:171], v[216:219], v[8:11]
	v_mfma_f32_16x16x32_bf16 v[40:43], v[172:175], v[188:191], v[40:43]
	v_mfma_f32_16x16x32_bf16 v[36:39], v[180:183], v[188:191], v[36:39]
	v_mfma_f32_16x16x32_bf16 v[28:31], v[172:175], v[196:199], v[28:31]
	v_mfma_f32_16x16x32_bf16 v[24:27], v[180:183], v[196:199], v[24:27]
	v_mfma_f32_16x16x32_bf16 v[16:19], v[172:175], v[204:207], v[16:19]
	v_mfma_f32_16x16x32_bf16 v[12:15], v[180:183], v[204:207], v[12:15]
	v_mfma_f32_16x16x32_bf16 v[4:7], v[172:175], v[212:215], v[4:7]
	v_mfma_f32_16x16x32_bf16 v[0:3], v[180:183], v[212:215], v[0:3]
	v_mfma_f32_16x16x32_bf16 v[40:43], v[176:179], v[192:195], v[40:43]
	v_mfma_f32_16x16x32_bf16 v[36:39], v[184:187], v[192:195], v[36:39]
	v_mfma_f32_16x16x32_bf16 v[28:31], v[176:179], v[200:203], v[28:31]
	v_mfma_f32_16x16x32_bf16 v[24:27], v[184:187], v[200:203], v[24:27]
	v_mfma_f32_16x16x32_bf16 v[16:19], v[176:179], v[208:211], v[16:19]
	v_mfma_f32_16x16x32_bf16 v[12:15], v[184:187], v[208:211], v[12:15]
	v_mfma_f32_16x16x32_bf16 v[4:7], v[176:179], v[216:219], v[4:7]
	v_mfma_f32_16x16x32_bf16 v[0:3], v[184:187], v[216:219], v[0:3]
	s_setprio 0
	s_barrier
	s_add_i32 s56, s56, 2
	s_add_u32 s20, s20, 0x100
	s_addc_u32 s21, s21, 0
	s_add_u32 s54, s54, 0x100
	s_addc_u32 s55, s55, 0
	s_cmp_gt_u32 s56, 13
	s_cbranch_scc0 .LBB0_564
.LBB0_564:
	ds_read_b128 v[150:153], v156
	ds_read_b128 v[160:163], v156 offset:1024
	ds_read_b128 v[164:167], v156 offset:2048
	ds_read_b128 v[168:171], v156 offset:3072
	ds_read_b128 v[172:175], v157
	ds_read_b128 v[176:179], v157 offset:1024
	ds_read_b128 v[180:183], v157 offset:2048
	ds_read_b128 v[184:187], v157 offset:3072
	s_add_u32 s22, s20, 0xfffc0080
	s_addc_u32 s23, s21, -1
	s_cmp_eq_u32 s56, 12
	s_cselect_b32 s25, s13, s23
	s_cselect_b32 s24, s15, s22
	s_cselect_b32 s23, s26, s55
	s_cselect_b32 s22, s27, s54
	v_lshl_add_u64 v[220:221], s[20:21], 0, v[142:143]
	s_add_i32 m0, s35, 0xc000
	ds_read_b128 v[188:191], v158
	ds_read_b128 v[192:195], v158 offset:1024
	ds_read_b128 v[196:199], v158 offset:2048
	ds_read_b128 v[200:203], v158 offset:3072
	ds_read_b128 v[204:207], v158 offset:4096
	ds_read_b128 v[208:211], v158 offset:5120
	ds_read_b128 v[212:215], v158 offset:6144
	ds_read_b128 v[216:219], v158 offset:7168
	global_load_lds_dwordx4 v[220:221], off
	v_lshl_add_u64 v[220:221], s[20:21], 0, v[144:145]
	s_add_i32 m0, s35, 0xe000
	s_nop 0
	global_load_lds_dwordx4 v[220:221], off
	s_waitcnt vmcnt(8)
	s_waitcnt lgkmcnt(0)
	s_barrier
; #define PG8_STAGE(bufoff, gbase, voff) do { _Pragma("unroll") for (int _i = 0; _i < 2; ++_i) \
;         __builtin_amdgcn_global_load_lds((const unsigned*)((const char*)(gbase) + (voff)[_i]), (LAS unsigned*)(lds + (bufoff) + ldsw + _i * 8192), 16, 0, 0); } while (0)
; #define PG8_LDA(dst, b, h) do { _Pragma("unroll") for (int m = 0; m < 4; ++m) _Pragma("unroll") for (int k = 0; k < 2; ++k) dst[m][k] = *(const LAS bf16x8*)(lds + PG8_SA(b, h) + aoff + m * 2048 + k * 1024); } while (0)
; #define PG8_MMA(ai, bj, At, Bt) do { __builtin_amdgcn_s_setprio(1); _Pragma("unroll") for (int m = 0; m < 4; ++m) _Pragma("unroll") for (int n = 0; n < 2; ++n) _Pragma("unroll") for (int k = 0; k < 2; ++k) \
;         acc[ai][bj][m][n] = __builtin_amdgcn_mfma_f32_16x16x32_bf16(Bt[n][k], At[m][k], acc[ai][bj][m][n], 0, 0, 0); __builtin_amdgcn_s_setprio(0); } while (0)
; #define PG8_WAIT_V(n) asm volatile("s_waitcnt vmcnt(" #n ")" ::: "memory")
; #define PG8_WAIT_L(n) asm volatile("s_waitcnt lgkmcnt(" #n ")" ::: "memory")
; #define PG8_BAR __builtin_amdgcn_s_barrier()
; #define PG8_SCHED __builtin_amdgcn_sched_barrier(0)
; template <class Epi, class Sched>
; __device__ __forceinline__ void gemm_phase(LAS unsigned char* lds, const Sched& S, const Epi& E, bool natural = false) {
;     ...
;             PG8_WAIT_V(8); PG8_WAIT_L(0); PG8_BAR; PG8_MMA(0, 0, At, B0); PG8_MMA(0, 1, At, B1); PG8_BAR; PG8_SCHED;
;             PG8_LDA(At, 0, 1); PG8_STAGE(PG8_SB(0, 0), b2, voffB0); PG8_STAGE(PG8_SB(0, 1), b2, voffB1); PG8_STAGE(PG8_SA(0, 0), a2, voffA);
;             PG8_WAIT_V(8); PG8_WAIT_L(0); PG8_BAR; PG8_MMA(1, 0, At, B0); PG8_MMA(1, 1, At, B1); PG8_BAR; PG8_SCHED;
	s_setprio 1
	s_waitcnt lgkmcnt(0)
	v_mfma_f32_16x16x32_bf16 v[124:127], v[150:153], v[188:191], v[124:127]
	v_mfma_f32_16x16x32_bf16 v[120:123], v[164:167], v[188:191], v[120:123]
	v_mfma_f32_16x16x32_bf16 v[116:119], v[150:153], v[196:199], v[116:119]
	v_mfma_f32_16x16x32_bf16 v[112:115], v[164:167], v[196:199], v[112:115]
	v_mfma_f32_16x16x32_bf16 v[104:107], v[150:153], v[204:207], v[104:107]
	v_mfma_f32_16x16x32_bf16 v[96:99], v[164:167], v[204:207], v[96:99]
	v_mfma_f32_16x16x32_bf16 v[88:91], v[150:153], v[212:215], v[88:91]
	v_mfma_f32_16x16x32_bf16 v[80:83], v[164:167], v[212:215], v[80:83]
	v_mfma_f32_16x16x32_bf16 v[124:127], v[160:163], v[192:195], v[124:127]
	v_mfma_f32_16x16x32_bf16 v[120:123], v[168:171], v[192:195], v[120:123]
	v_mfma_f32_16x16x32_bf16 v[116:119], v[160:163], v[200:203], v[116:119]
	v_mfma_f32_16x16x32_bf16 v[112:115], v[168:171], v[200:203], v[112:115]
	v_mfma_f32_16x16x32_bf16 v[104:107], v[160:163], v[208:211], v[104:107]
	v_mfma_f32_16x16x32_bf16 v[96:99], v[168:171], v[208:211], v[96:99]
	v_mfma_f32_16x16x32_bf16 v[88:91], v[160:163], v[216:219], v[88:91]
	v_mfma_f32_16x16x32_bf16 v[80:83], v[168:171], v[216:219], v[80:83]
	v_mfma_f32_16x16x32_bf16 v[108:111], v[172:175], v[188:191], v[108:111]
	v_mfma_f32_16x16x32_bf16 v[100:103], v[180:183], v[188:191], v[100:103]
	v_mfma_f32_16x16x32_bf16 v[92:95], v[172:175], v[196:199], v[92:95]
	v_mfma_f32_16x16x32_bf16 v[84:87], v[180:183], v[196:199], v[84:87]
	v_mfma_f32_16x16x32_bf16 v[76:79], v[172:175], v[204:207], v[76:79]
	v_mfma_f32_16x16x32_bf16 v[72:75], v[180:183], v[204:207], v[72:75]
	v_mfma_f32_16x16x32_bf16 v[68:71], v[172:175], v[212:215], v[68:71]
	v_mfma_f32_16x16x32_bf16 v[64:67], v[180:183], v[212:215], v[64:67]
	v_mfma_f32_16x16x32_bf16 v[108:111], v[176:179], v[192:195], v[108:111]
	v_mfma_f32_16x16x32_bf16 v[100:103], v[184:187], v[192:195], v[100:103]
	v_mfma_f32_16x16x32_bf16 v[92:95], v[176:179], v[200:203], v[92:95]
	v_mfma_f32_16x16x32_bf16 v[84:87], v[184:187], v[200:203], v[84:87]
	v_mfma_f32_16x16x32_bf16 v[76:79], v[176:179], v[208:211], v[76:79]
	v_mfma_f32_16x16x32_bf16 v[72:75], v[184:187], v[208:211], v[72:75]
	v_mfma_f32_16x16x32_bf16 v[68:71], v[176:179], v[216:219], v[68:71]
	v_mfma_f32_16x16x32_bf16 v[64:67], v[184:187], v[216:219], v[64:67]
	s_setprio 0
	s_barrier
	s_add_i32 s57, s44, s31
	v_lshl_add_u64 v[220:221], s[22:23], 0, v[136:137]
	s_mov_b32 m0, s57
	ds_read_b128 v[188:191], v158 offset:16384
	ds_read_b128 v[192:195], v158 offset:17408
	ds_read_b128 v[196:199], v158 offset:18432
	ds_read_b128 v[200:203], v158 offset:19456
	ds_read_b128 v[204:207], v158 offset:20480
	ds_read_b128 v[208:211], v158 offset:21504
	ds_read_b128 v[212:215], v158 offset:22528
	ds_read_b128 v[216:219], v158 offset:23552
	global_load_lds_dwordx4 v[220:221], off
	v_lshl_add_u64 v[222:223], s[22:23], 0, v[130:131]
	s_add_i32 m0, s57, 0x2000
	s_add_i32 s57, s45, s31
	global_load_lds_dwordx4 v[222:223], off
	v_lshl_add_u64 v[224:225], s[22:23], 0, v[134:135]
	s_mov_b32 m0, s57
	v_lshl_add_u64 v[226:227], s[24:25], 0, v[132:133]
	global_load_lds_dwordx4 v[224:225], off
	v_lshl_add_u64 v[224:225], s[22:23], 0, v[128:129]
	s_add_i32 m0, s57, 0x2000
	s_nop 0
	global_load_lds_dwordx4 v[224:225], off
	v_lshl_add_u64 v[224:225], s[24:25], 0, v[138:139]
	s_mov_b32 m0, s35
	s_nop 0
	global_load_lds_dwordx4 v[224:225], off
	s_mov_b32 m0, s36
	s_nop 0
	global_load_lds_dwordx4 v[226:227], off
	s_waitcnt vmcnt(8)
	s_waitcnt lgkmcnt(0)
	s_barrier
	s_setprio 1
	s_waitcnt lgkmcnt(0)
	v_mfma_f32_16x16x32_bf16 v[60:63], v[150:153], v[188:191], v[60:63]
	v_mfma_f32_16x16x32_bf16 v[56:59], v[164:167], v[188:191], v[56:59]
	v_mfma_f32_16x16x32_bf16 v[52:55], v[150:153], v[196:199], v[52:55]
	v_mfma_f32_16x16x32_bf16 v[48:51], v[164:167], v[196:199], v[48:51]
	v_mfma_f32_16x16x32_bf16 v[44:47], v[150:153], v[204:207], v[44:47]
	v_mfma_f32_16x16x32_bf16 v[32:35], v[164:167], v[204:207], v[32:35]
	v_mfma_f32_16x16x32_bf16 v[20:23], v[150:153], v[212:215], v[20:23]
	v_mfma_f32_16x16x32_bf16 v[8:11], v[164:167], v[212:215], v[8:11]
	v_mfma_f32_16x16x32_bf16 v[60:63], v[160:163], v[192:195], v[60:63]
	v_mfma_f32_16x16x32_bf16 v[56:59], v[168:171], v[192:195], v[56:59]
	v_mfma_f32_16x16x32_bf16 v[52:55], v[160:163], v[200:203], v[52:55]
	v_mfma_f32_16x16x32_bf16 v[48:51], v[168:171], v[200:203], v[48:51]
	v_mfma_f32_16x16x32_bf16 v[44:47], v[160:163], v[208:211], v[44:47]
	v_mfma_f32_16x16x32_bf16 v[32:35], v[168:171], v[208:211], v[32:35]
	v_mfma_f32_16x16x32_bf16 v[20:23], v[160:163], v[216:219], v[20:23]
	v_mfma_f32_16x16x32_bf16 v[8:11], v[168:171], v[216:219], v[8:11]
	v_mfma_f32_16x16x32_bf16 v[40:43], v[172:175], v[188:191], v[40:43]
	v_mfma_f32_16x16x32_bf16 v[36:39], v[180:183], v[188:191], v[36:39]
	v_mfma_f32_16x16x32_bf16 v[28:31], v[172:175], v[196:199], v[28:31]
	v_mfma_f32_16x16x32_bf16 v[24:27], v[180:183], v[196:199], v[24:27]
	v_mfma_f32_16x16x32_bf16 v[16:19], v[172:175], v[204:207], v[16:19]
	v_mfma_f32_16x16x32_bf16 v[12:15], v[180:183], v[204:207], v[12:15]
	v_mfma_f32_16x16x32_bf16 v[4:7], v[172:175], v[212:215], v[4:7]
	v_mfma_f32_16x16x32_bf16 v[0:3], v[180:183], v[212:215], v[0:3]
	v_mfma_f32_16x16x32_bf16 v[40:43], v[176:179], v[192:195], v[40:43]
	v_mfma_f32_16x16x32_bf16 v[36:39], v[184:187], v[192:195], v[36:39]
	v_mfma_f32_16x16x32_bf16 v[28:31], v[176:179], v[200:203], v[28:31]
	v_mfma_f32_16x16x32_bf16 v[24:27], v[184:187], v[200:203], v[24:27]
	v_mfma_f32_16x16x32_bf16 v[16:19], v[176:179], v[208:211], v[16:19]
	v_mfma_f32_16x16x32_bf16 v[12:15], v[184:187], v[208:211], v[12:15]
	v_mfma_f32_16x16x32_bf16 v[4:7], v[176:179], v[216:219], v[4:7]
	v_mfma_f32_16x16x32_bf16 v[0:3], v[184:187], v[216:219], v[0:3]
	s_setprio 0
	s_barrier
; #define PG8_STAGE(bufoff, gbase, voff) do { _Pragma("unroll") for (int _i = 0; _i < 2; ++_i) \
;         __builtin_amdgcn_global_load_lds((const unsigned*)((const char*)(gbase) + (voff)[_i]), (LAS unsigned*)(lds + (bufoff) + ldsw + _i * 8192), 16, 0, 0); } while (0)
; #define PG8_LDA(dst, b, h) do { _Pragma("unroll") for (int m = 0; m < 4; ++m) _Pragma("unroll") for (int k = 0; k < 2; ++k) dst[m][k] = *(const LAS bf16x8*)(lds + PG8_SA(b, h) + aoff + m * 2048 + k * 1024); } while (0)
; #define PG8_LDB(dst, b, h) do { _Pragma("unroll") for (int n = 0; n < 2; ++n) _Pragma("unroll") for (int k = 0; k < 2; ++k) dst[n][k] = *(const LAS bf16x8*)(lds + PG8_SB(b, h) + boff + n * 2048 + k * 1024); } while (0)
; #define PG8_MMA(ai, bj, At, Bt) do { __builtin_amdgcn_s_setprio(1); _Pragma("unroll") for (int m = 0; m < 4; ++m) _Pragma("unroll") for (int n = 0; n < 2; ++n) _Pragma("unroll") for (int k = 0; k < 2; ++k) \
;         acc[ai][bj][m][n] = __builtin_amdgcn_mfma_f32_16x16x32_bf16(Bt[n][k], At[m][k], acc[ai][bj][m][n], 0, 0, 0); __builtin_amdgcn_s_setprio(0); } while (0)
; #define PG8_WAIT_V(n) asm volatile("s_waitcnt vmcnt(" #n ")" ::: "memory")
; #define PG8_WAIT_L(n) asm volatile("s_waitcnt lgkmcnt(" #n ")" ::: "memory")
; #define PG8_BAR __builtin_amdgcn_s_barrier()
; #define PG8_SCHED __builtin_amdgcn_sched_barrier(0)
; template <class Epi, class Sched>
; __device__ __forceinline__ void gemm_phase(LAS unsigned char* lds, const Sched& S, const Epi& E, bool natural = false) {
;     ...
;             PG8_LDB(B0, 1, 0); PG8_LDB(B1, 1, 1); PG8_SCHED; PG8_LDA(At, 1, 0); PG8_STAGE(PG8_SA(0, 1), a2 + hstep, voffA);
;             PG8_WAIT_V(8); PG8_WAIT_L(0); PG8_BAR; PG8_MMA(0, 0, At, B0); PG8_MMA(0, 1, At, B1); PG8_BAR; PG8_SCHED;
	s_add_i32 s57, 0, 0x18000
	v_add_u32_e32 v140, s57, v154
	s_add_i32 s58, 0, 0x1c000
	ds_read_b128 v[150:153], v140
	ds_read_b128 v[160:163], v140 offset:1024
	ds_read_b128 v[164:167], v140 offset:2048
	ds_read_b128 v[168:171], v140 offset:3072
	v_add_u32_e32 v140, s58, v154
	ds_read_b128 v[172:175], v140
	ds_read_b128 v[176:179], v140 offset:1024
	ds_read_b128 v[180:183], v140 offset:2048
	ds_read_b128 v[184:187], v140 offset:3072
	s_add_u32 s24, s24, 0x40000
	s_addc_u32 s25, s25, 0
	s_mov_b32 m0, s37
	v_lshl_add_u64 v[228:229], s[24:25], 0, v[138:139]
	ds_read_b128 v[188:191], v158 offset:32768
	ds_read_b128 v[192:195], v158 offset:33792
	ds_read_b128 v[196:199], v158 offset:34816
	ds_read_b128 v[200:203], v158 offset:35840
	ds_read_b128 v[204:207], v158 offset:36864
	ds_read_b128 v[208:211], v158 offset:37888
	ds_read_b128 v[212:215], v158 offset:38912
	ds_read_b128 v[216:219], v158 offset:39936
	global_load_lds_dwordx4 v[228:229], off
	v_lshl_add_u64 v[228:229], s[24:25], 0, v[132:133]
	s_mov_b32 m0, s38
	s_nop 0
	global_load_lds_dwordx4 v[228:229], off
	s_waitcnt vmcnt(8)
	s_waitcnt lgkmcnt(0)
	s_barrier
	s_setprio 1
	s_waitcnt lgkmcnt(0)
	v_mfma_f32_16x16x32_bf16 v[124:127], v[150:153], v[188:191], v[124:127]
	v_mfma_f32_16x16x32_bf16 v[120:123], v[164:167], v[188:191], v[120:123]
	v_mfma_f32_16x16x32_bf16 v[116:119], v[150:153], v[196:199], v[116:119]
	v_mfma_f32_16x16x32_bf16 v[112:115], v[164:167], v[196:199], v[112:115]
	v_mfma_f32_16x16x32_bf16 v[104:107], v[150:153], v[204:207], v[104:107]
	v_mfma_f32_16x16x32_bf16 v[96:99], v[164:167], v[204:207], v[96:99]
	v_mfma_f32_16x16x32_bf16 v[88:91], v[150:153], v[212:215], v[88:91]
	v_mfma_f32_16x16x32_bf16 v[80:83], v[164:167], v[212:215], v[80:83]
	v_mfma_f32_16x16x32_bf16 v[124:127], v[160:163], v[192:195], v[124:127]
	v_mfma_f32_16x16x32_bf16 v[120:123], v[168:171], v[192:195], v[120:123]
	v_mfma_f32_16x16x32_bf16 v[116:119], v[160:163], v[200:203], v[116:119]
	v_mfma_f32_16x16x32_bf16 v[112:115], v[168:171], v[200:203], v[112:115]
	v_mfma_f32_16x16x32_bf16 v[104:107], v[160:163], v[208:211], v[104:107]
	v_mfma_f32_16x16x32_bf16 v[96:99], v[168:171], v[208:211], v[96:99]
	v_mfma_f32_16x16x32_bf16 v[88:91], v[160:163], v[216:219], v[88:91]
	v_mfma_f32_16x16x32_bf16 v[80:83], v[168:171], v[216:219], v[80:83]
	v_mfma_f32_16x16x32_bf16 v[108:111], v[172:175], v[188:191], v[108:111]
	v_mfma_f32_16x16x32_bf16 v[100:103], v[180:183], v[188:191], v[100:103]
	v_mfma_f32_16x16x32_bf16 v[92:95], v[172:175], v[196:199], v[92:95]
	v_mfma_f32_16x16x32_bf16 v[84:87], v[180:183], v[196:199], v[84:87]
	v_mfma_f32_16x16x32_bf16 v[76:79], v[172:175], v[204:207], v[76:79]
	v_mfma_f32_16x16x32_bf16 v[72:75], v[180:183], v[204:207], v[72:75]
	v_mfma_f32_16x16x32_bf16 v[68:71], v[172:175], v[212:215], v[68:71]
	v_mfma_f32_16x16x32_bf16 v[64:67], v[180:183], v[212:215], v[64:67]
	v_mfma_f32_16x16x32_bf16 v[108:111], v[176:179], v[192:195], v[108:111]
	v_mfma_f32_16x16x32_bf16 v[100:103], v[184:187], v[192:195], v[100:103]
	v_mfma_f32_16x16x32_bf16 v[92:95], v[176:179], v[200:203], v[92:95]
	v_mfma_f32_16x16x32_bf16 v[84:87], v[184:187], v[200:203], v[84:87]
	v_mfma_f32_16x16x32_bf16 v[76:79], v[176:179], v[208:211], v[76:79]
	v_mfma_f32_16x16x32_bf16 v[72:75], v[184:187], v[208:211], v[72:75]
	v_mfma_f32_16x16x32_bf16 v[68:71], v[176:179], v[216:219], v[68:71]
	v_mfma_f32_16x16x32_bf16 v[64:67], v[184:187], v[216:219], v[64:67]
	s_setprio 0
	s_barrier
; #define PG8_STAGE(bufoff, gbase, voff) do { _Pragma("unroll") for (int _i = 0; _i < 2; ++_i) \
;         __builtin_amdgcn_global_load_lds((const unsigned*)((const char*)(gbase) + (voff)[_i]), (LAS unsigned*)(lds + (bufoff) + ldsw + _i * 8192), 16, 0, 0); } while (0)
; #define PG8_LDA(dst, b, h) do { _Pragma("unroll") for (int m = 0; m < 4; ++m) _Pragma("unroll") for (int k = 0; k < 2; ++k) dst[m][k] = *(const LAS bf16x8*)(lds + PG8_SA(b, h) + aoff + m * 2048 + k * 1024); } while (0)
; #define PG8_MMA(ai, bj, At, Bt) do { __builtin_amdgcn_s_setprio(1); _Pragma("unroll") for (int m = 0; m < 4; ++m) _Pragma("unroll") for (int n = 0; n < 2; ++n) _Pragma("unroll") for (int k = 0; k < 2; ++k) \
;         acc[ai][bj][m][n] = __builtin_amdgcn_mfma_f32_16x16x32_bf16(Bt[n][k], At[m][k], acc[ai][bj][m][n], 0, 0, 0); __builtin_amdgcn_s_setprio(0); } while (0)
; #define PG8_WAIT_V(n) asm volatile("s_waitcnt vmcnt(" #n ")" ::: "memory")
; #define PG8_WAIT_L(n) asm volatile("s_waitcnt lgkmcnt(" #n ")" ::: "memory")
; #define PG8_BAR __builtin_amdgcn_s_barrier()
; #define PG8_SCHED __builtin_amdgcn_sched_barrier(0)
; template <class Epi, class Sched>
; __device__ __forceinline__ void gemm_phase(LAS unsigned char* lds, const Sched& S, const Epi& E, bool natural = false) {
;     ...
;             PG8_LDA(At, 1, 1); PG8_STAGE(PG8_SB(1, 0), b3, voffB0); PG8_STAGE(PG8_SB(1, 1), b3, voffB1); PG8_STAGE(PG8_SA(1, 0), a3, voffA);
;             PG8_WAIT_V(8); PG8_WAIT_L(0); PG8_BAR; PG8_MMA(1, 0, At, B0); PG8_MMA(1, 1, At, B1); PG8_BAR; PG8_SCHED;
;         }
;         if (wr == 0) PG8_BAR;
	s_add_u32 s22, s22, 0x80
	s_addc_u32 s23, s23, 0
	s_add_i32 s24, s57, s31
	v_lshl_add_u64 v[220:221], v[220:221], 0, s[8:9]
	s_mov_b32 m0, s24
	ds_read_b128 v[188:191], v158 offset:49152
	ds_read_b128 v[192:195], v158 offset:50176
	ds_read_b128 v[196:199], v158 offset:51200
	ds_read_b128 v[200:203], v158 offset:52224
	ds_read_b128 v[204:207], v158 offset:53248
	ds_read_b128 v[208:211], v158 offset:54272
	ds_read_b128 v[212:215], v158 offset:55296
	ds_read_b128 v[216:219], v158 offset:56320
	global_load_lds_dwordx4 v[220:221], off
	v_lshl_add_u64 v[220:221], v[222:223], 0, s[8:9]
	s_add_i32 m0, s24, 0x2000
	s_add_i32 s24, s58, s31
	global_load_lds_dwordx4 v[220:221], off
	v_lshl_add_u64 v[220:221], s[22:23], 0, v[134:135]
	s_mov_b32 m0, s24
	s_nop 0
	global_load_lds_dwordx4 v[220:221], off
	v_lshl_add_u64 v[220:221], s[22:23], 0, v[128:129]
	s_add_i32 m0, s24, 0x2000
	s_nop 0
	global_load_lds_dwordx4 v[220:221], off
	v_lshl_add_u64 v[220:221], v[224:225], 0, s[8:9]
	s_mov_b32 m0, s41
	s_nop 0
	global_load_lds_dwordx4 v[220:221], off
	v_lshl_add_u64 v[220:221], v[226:227], 0, s[8:9]
	s_mov_b32 m0, s42
	s_nop 0
	global_load_lds_dwordx4 v[220:221], off
	s_waitcnt vmcnt(8)
	s_waitcnt lgkmcnt(0)
	s_barrier
	s_setprio 1
	s_waitcnt lgkmcnt(0)
	v_mfma_f32_16x16x32_bf16 v[60:63], v[150:153], v[188:191], v[60:63]
	v_mfma_f32_16x16x32_bf16 v[56:59], v[164:167], v[188:191], v[56:59]
	v_mfma_f32_16x16x32_bf16 v[52:55], v[150:153], v[196:199], v[52:55]
	v_mfma_f32_16x16x32_bf16 v[48:51], v[164:167], v[196:199], v[48:51]
	v_mfma_f32_16x16x32_bf16 v[44:47], v[150:153], v[204:207], v[44:47]
	v_mfma_f32_16x16x32_bf16 v[32:35], v[164:167], v[204:207], v[32:35]
	v_mfma_f32_16x16x32_bf16 v[20:23], v[150:153], v[212:215], v[20:23]
	v_mfma_f32_16x16x32_bf16 v[8:11], v[164:167], v[212:215], v[8:11]
	v_mfma_f32_16x16x32_bf16 v[60:63], v[160:163], v[192:195], v[60:63]
	v_mfma_f32_16x16x32_bf16 v[56:59], v[168:171], v[192:195], v[56:59]
	v_mfma_f32_16x16x32_bf16 v[52:55], v[160:163], v[200:203], v[52:55]
	v_mfma_f32_16x16x32_bf16 v[48:51], v[168:171], v[200:203], v[48:51]
	v_mfma_f32_16x16x32_bf16 v[44:47], v[160:163], v[208:211], v[44:47]
	v_mfma_f32_16x16x32_bf16 v[32:35], v[168:171], v[208:211], v[32:35]
	v_mfma_f32_16x16x32_bf16 v[20:23], v[160:163], v[216:219], v[20:23]
	v_mfma_f32_16x16x32_bf16 v[8:11], v[168:171], v[216:219], v[8:11]
	v_mfma_f32_16x16x32_bf16 v[40:43], v[172:175], v[188:191], v[40:43]
	v_mfma_f32_16x16x32_bf16 v[36:39], v[180:183], v[188:191], v[36:39]
	v_mfma_f32_16x16x32_bf16 v[28:31], v[172:175], v[196:199], v[28:31]
	v_mfma_f32_16x16x32_bf16 v[24:27], v[180:183], v[196:199], v[24:27]
	v_mfma_f32_16x16x32_bf16 v[16:19], v[172:175], v[204:207], v[16:19]
	v_mfma_f32_16x16x32_bf16 v[12:15], v[180:183], v[204:207], v[12:15]
	v_mfma_f32_16x16x32_bf16 v[4:7], v[172:175], v[212:215], v[4:7]
	v_mfma_f32_16x16x32_bf16 v[0:3], v[180:183], v[212:215], v[0:3]
	v_mfma_f32_16x16x32_bf16 v[40:43], v[176:179], v[192:195], v[40:43]
	v_mfma_f32_16x16x32_bf16 v[36:39], v[184:187], v[192:195], v[36:39]
	v_mfma_f32_16x16x32_bf16 v[28:31], v[176:179], v[200:203], v[28:31]
	v_mfma_f32_16x16x32_bf16 v[24:27], v[184:187], v[200:203], v[24:27]
	v_mfma_f32_16x16x32_bf16 v[16:19], v[176:179], v[208:211], v[16:19]
	v_mfma_f32_16x16x32_bf16 v[12:15], v[184:187], v[208:211], v[12:15]
	v_mfma_f32_16x16x32_bf16 v[4:7], v[176:179], v[216:219], v[4:7]
	v_mfma_f32_16x16x32_bf16 v[0:3], v[184:187], v[216:219], v[0:3]
	s_setprio 0
	s_barrier
	s_add_i32 s56, s56, 2
	s_add_u32 s20, s20, 0x100
	s_addc_u32 s21, s21, 0
	s_add_u32 s54, s54, 0x100
	s_addc_u32 s55, s55, 0
	s_cmp_gt_u32 s56, 13
	s_cbranch_scc0 .LBB0_564
	s_and_b64 vcc, exec, s[10:11]
	s_cbranch_vccz .LBB0_567
	s_barrier
